# LN row-stat cross-lane sums via v_permlane16/32_swap instead of 32 serialized ds_bpermute round trips (on top of v26)
# baseline (speedup 1.0000x reference)
;     __device__ __forceinline__ void fused(f32x4 (&acc)[2][2][4][2], const Unit& u, int wr, int wc, int fr, int fq, PG8_LAS unsigned char* lds, int wid, int lane) const {
;     ...
;         const int col0 = u.pn * 256 + wc * 32 + 4 * fq, rowb = u.pm * 256 + wr * 64 + fr;
;         const float* gate = ada + (size_t)((u.pm * 256) >> 11) * 3072 + 2048;
;         int zero = 0; asm volatile("" : "+v"(zero));
;         const float* xp = x + (size_t)(rowb + zero) * D + col0;
;         f32x4 xc[4], xn[4];
; #pragma unroll
;         for (int m = 0; m < 4; ++m) xc[m] = __builtin_nontemporal_load((const f32x4*)(xp + (size_t)(m * 16) * D));
; #pragma unroll
;         for (int g = 0; g < 8; ++g) { const int bj = g >> 2, n = (g >> 1) & 1, ai = g & 1; const int c = col0 + bj * 128 + n * 16;
;             if (g < 7) { const int g1 = g + 1, bj1 = g1 >> 2, n1 = (g1 >> 1) & 1, ai1 = g1 & 1;
; #pragma unroll
;                 for (int m = 0; m < 4; ++m) xn[m] = __builtin_nontemporal_load((const f32x4*)(xp + (size_t)(ai1 * 128 + m * 16) * D + bj1 * 128 + n1 * 16)); }
;             const f32x4 gv = *(const f32x4*)(gate + c), bv = *(const f32x4*)(bo + c);
;             asm volatile("" ::: "memory");
; #pragma unroll
;             for (int m = 0; m < 4; ++m) acc[ai][bj][m][n] = xc[m] * ALPHA + gv * (acc[ai][bj][m][n] + bv);
.LBB0_496:
	s_lshl_b32 s0, s39, 5
	s_lshl_b32 s1, s4, 8
	s_or_b32 s0, s1, s0
	v_lshrrev_b32_e32 v128, 2, v174
	v_and_or_b32 v166, v128, 12, s0
	s_lshl_b32 s6, s38, 8
	v_mov_b32_e32 v128, v149
	s_barrier
	v_add_u32_e32 v152, s6, v153
	v_add_u32_e32 v128, v128, v152
	v_ashrrev_i32_e32 v129, 31, v128
	v_lshlrev_b64 v[128:129], 12, v[128:129]
	v_ashrrev_i32_e32 v167, 31, v166
	s_ashr_i32 s0, s38, 3
	v_lshlrev_b64 v[154:155], 2, v[166:167]
	v_lshl_add_u64 v[128:129], s[76:77], 0, v[128:129]
	s_mul_hi_i32 s1, s0, 0x3000
	s_mulk_i32 s0, 0x3000
	v_lshl_add_u64 v[140:141], v[128:129], 0, v[154:155]
	s_add_u32 s0, s96, s0
	v_add_co_u32_e32 v136, vcc, s51, v140
	s_addc_u32 s1, s97, s1
	v_readlane_b32 s60, v250, 0
	v_addc_co_u32_e32 v137, vcc, 0, v141, vcc
	v_readlane_b32 s64, v250, 4
	v_readlane_b32 s65, v250, 5
	s_add_u32 s0, s0, 0x2000
	v_add_co_u32_e32 v128, vcc, s52, v140
	v_lshl_add_u64 v[156:157], s[64:65], 0, v[154:155]
	s_addc_u32 s1, s1, 0
	v_addc_co_u32_e32 v129, vcc, 0, v141, vcc
	global_load_dwordx4 v[132:135], v[156:157], off
	v_lshl_add_u64 v[138:139], s[0:1], 0, v[154:155]
	v_add_co_u32_e32 v130, vcc, s53, v140
	global_load_dwordx4 v[176:179], v[138:139], off
	s_nop 0
	v_addc_co_u32_e32 v131, vcc, 0, v141, vcc
	global_load_dwordx4 v[180:183], v[140:141], off nt
	global_load_dwordx4 v[184:187], v[136:137], off nt
	global_load_dwordx4 v[188:191], v[128:129], off nt
	global_load_dwordx4 v[192:195], v[130:131], off nt
	v_add_co_u32_e32 v158, vcc, s54, v140
	v_xor_b32_e32 v148, 16, v172
	s_nop 0
	v_addc_co_u32_e32 v159, vcc, 0, v141, vcc
	v_add_co_u32_e32 v160, vcc, s55, v140
	v_readlane_b32 s61, v250, 1
	s_nop 0
	v_addc_co_u32_e32 v161, vcc, 0, v141, vcc
	v_add_co_u32_e32 v162, vcc, s56, v140
	v_readlane_b32 s62, v250, 2
	s_nop 0
	v_addc_co_u32_e32 v163, vcc, 0, v141, vcc
	v_add_co_u32_e32 v164, vcc, s57, v140
	v_readlane_b32 s63, v250, 3
	s_nop 0
	v_addc_co_u32_e32 v165, vcc, 0, v141, vcc
	global_load_dwordx4 v[196:199], v[158:159], off nt
	global_load_dwordx4 v[200:203], v[160:161], off nt
	global_load_dwordx4 v[204:207], v[162:163], off nt
	global_load_dwordx4 v[208:211], v[164:165], off nt
	v_readlane_b32 s66, v250, 6
	v_readlane_b32 s67, v250, 7
	s_waitcnt vmcnt(0)
	v_pk_add_f32 v[82:83], v[82:83], v[134:135]
	v_pk_add_f32 v[80:81], v[80:81], v[132:133]
	v_pk_add_f32 v[78:79], v[78:79], v[134:135]
	v_pk_add_f32 v[76:77], v[76:77], v[132:133]
	v_pk_add_f32 v[66:67], v[66:67], v[134:135]
	v_pk_add_f32 v[64:65], v[64:65], v[132:133]
	v_pk_add_f32 v[62:63], v[62:63], v[134:135]
	v_pk_add_f32 v[60:61], v[60:61], v[132:133]
	v_pk_mul_f32 v[82:83], v[178:179], v[82:83]
	v_pk_mul_f32 v[80:81], v[176:177], v[80:81]
	v_pk_mul_f32 v[78:79], v[178:179], v[78:79]
	v_pk_mul_f32 v[76:77], v[176:177], v[76:77]
	v_pk_mul_f32 v[66:67], v[178:179], v[66:67]
	v_pk_mul_f32 v[64:65], v[176:177], v[64:65]
	v_pk_mul_f32 v[132:133], v[178:179], v[62:63]
	v_pk_mul_f32 v[134:135], v[176:177], v[60:61]
	v_pk_fma_f32 v[82:83], v[182:183], s[34:35], v[82:83] op_sel_hi:[1,0,1]
	v_pk_fma_f32 v[80:81], v[180:181], s[34:35], v[80:81] op_sel_hi:[1,0,1]
	v_pk_fma_f32 v[78:79], v[186:187], s[34:35], v[78:79] op_sel_hi:[1,0,1]
	v_pk_fma_f32 v[76:77], v[184:185], s[34:35], v[76:77] op_sel_hi:[1,0,1]
	v_pk_fma_f32 v[62:63], v[190:191], s[34:35], v[66:67] op_sel_hi:[1,0,1]
	v_pk_fma_f32 v[60:61], v[188:189], s[34:35], v[64:65] op_sel_hi:[1,0,1]
	v_pk_fma_f32 v[66:67], v[194:195], s[34:35], v[132:133] op_sel_hi:[1,0,1]
	v_pk_fma_f32 v[64:65], v[192:193], s[34:35], v[134:135] op_sel_hi:[1,0,1]
	s_nop 0
	global_load_dwordx4 v[132:135], v[156:157], off
	global_load_dwordx4 v[176:179], v[138:139], off
	global_load_dwordx4 v[180:183], v[130:131], off offset:64 nt
	global_load_dwordx4 v[184:187], v[128:129], off offset:64 nt
	global_load_dwordx4 v[188:191], v[136:137], off offset:64 nt
	global_load_dwordx4 v[192:195], v[140:141], off offset:64 nt
	v_or_b32_e32 v138, 16, v166
	v_ashrrev_i32_e32 v139, 31, v138
	v_lshl_add_u64 v[138:139], v[138:139], 2, s[0:1]
	s_waitcnt vmcnt(5)
	v_pk_add_f32 v[94:95], v[94:95], v[134:135]
	v_pk_add_f32 v[92:93], v[92:93], v[132:133]
	v_pk_add_f32 v[90:91], v[90:91], v[134:135]
	v_pk_add_f32 v[88:89], v[88:89], v[132:133]
	v_pk_add_f32 v[46:47], v[46:47], v[134:135]
	v_pk_add_f32 v[44:45], v[44:45], v[132:133]
	v_pk_add_f32 v[30:31], v[30:31], v[134:135]
	v_pk_add_f32 v[28:29], v[28:29], v[132:133]
	s_waitcnt vmcnt(4)
	v_pk_mul_f32 v[94:95], v[178:179], v[94:95]
	v_pk_mul_f32 v[92:93], v[176:177], v[92:93]
	v_pk_mul_f32 v[90:91], v[178:179], v[90:91]
	v_pk_mul_f32 v[88:89], v[176:177], v[88:89]
	v_pk_mul_f32 v[46:47], v[178:179], v[46:47]
	v_pk_mul_f32 v[44:45], v[176:177], v[44:45]
	v_pk_mul_f32 v[30:31], v[178:179], v[30:31]
	v_pk_mul_f32 v[28:29], v[176:177], v[28:29]
	v_pk_fma_f32 v[94:95], v[210:211], s[34:35], v[94:95] op_sel_hi:[1,0,1]
	v_pk_fma_f32 v[92:93], v[208:209], s[34:35], v[92:93] op_sel_hi:[1,0,1]
	v_pk_fma_f32 v[90:91], v[206:207], s[34:35], v[90:91] op_sel_hi:[1,0,1]
	v_pk_fma_f32 v[88:89], v[204:205], s[34:35], v[88:89] op_sel_hi:[1,0,1]
	v_pk_fma_f32 v[46:47], v[202:203], s[34:35], v[46:47] op_sel_hi:[1,0,1]
	v_pk_fma_f32 v[44:45], v[200:201], s[34:35], v[44:45] op_sel_hi:[1,0,1]
	v_pk_fma_f32 v[30:31], v[198:199], s[34:35], v[30:31] op_sel_hi:[1,0,1]
	v_pk_fma_f32 v[28:29], v[196:197], s[34:35], v[28:29] op_sel_hi:[1,0,1]
	s_nop 0
	global_load_dwordx4 v[132:135], v[156:157], off offset:64
	global_load_dwordx4 v[176:179], v[138:139], off
	global_load_dwordx4 v[196:199], v[158:159], off offset:64 nt
	global_load_dwordx4 v[200:203], v[160:161], off offset:64 nt
	global_load_dwordx4 v[204:207], v[162:163], off offset:64 nt
	global_load_dwordx4 v[208:211], v[164:165], off offset:64 nt
	s_waitcnt vmcnt(5)
;     __device__ __forceinline__ void fused(f32x4 (&acc)[2][2][4][2], const Unit& u, int wr, int wc, int fr, int fq, PG8_LAS unsigned char* lds, int wid, int lane) const {
;     ...
;         for (int g = 0; g < 8; ++g) { const int bj = g >> 2, n = (g >> 1) & 1, ai = g & 1; const int c = col0 + bj * 128 + n * 16;
;             if (g < 7) { const int g1 = g + 1, bj1 = g1 >> 2, n1 = (g1 >> 1) & 1, ai1 = g1 & 1;
; #pragma unroll
;                 for (int m = 0; m < 4; ++m) xn[m] = __builtin_nontemporal_load((const f32x4*)(xp + (size_t)(ai1 * 128 + m * 16) * D + bj1 * 128 + n1 * 16)); }
;             const f32x4 gv = *(const f32x4*)(gate + c), bv = *(const f32x4*)(bo + c);
;             asm volatile("" ::: "memory");
; #pragma unroll
;             for (int m = 0; m < 4; ++m) acc[ai][bj][m][n] = xc[m] * ALPHA + gv * (acc[ai][bj][m][n] + bv);
;             asm volatile("" : "+v"(acc[ai][bj][0][n]), "+v"(acc[ai][bj][1][n]), "+v"(acc[ai][bj][2][n]), "+v"(acc[ai][bj][3][n]));
;             asm volatile("" ::: "memory");
; #pragma unroll
;             for (int m = 0; m < 4; ++m) xc[m] = xn[m]; }
	v_pk_add_f32 v[86:87], v[86:87], v[134:135]
	v_pk_add_f32 v[84:85], v[84:85], v[132:133]
	v_pk_add_f32 v[54:55], v[54:55], v[134:135]
	v_pk_add_f32 v[52:53], v[52:53], v[132:133]
	v_pk_add_f32 v[34:35], v[34:35], v[134:135]
	v_pk_add_f32 v[32:33], v[32:33], v[132:133]
	v_pk_add_f32 v[18:19], v[18:19], v[134:135]
	v_pk_add_f32 v[16:17], v[16:17], v[132:133]
	s_waitcnt vmcnt(4)
	v_pk_mul_f32 v[86:87], v[178:179], v[86:87]
	v_pk_mul_f32 v[84:85], v[176:177], v[84:85]
	v_pk_mul_f32 v[54:55], v[178:179], v[54:55]
	v_pk_mul_f32 v[52:53], v[176:177], v[52:53]
	v_pk_mul_f32 v[34:35], v[178:179], v[34:35]
	v_pk_mul_f32 v[32:33], v[176:177], v[32:33]
	v_pk_mul_f32 v[18:19], v[178:179], v[18:19]
	v_pk_mul_f32 v[16:17], v[176:177], v[16:17]
	v_pk_fma_f32 v[86:87], v[194:195], s[34:35], v[86:87] op_sel_hi:[1,0,1]
	v_pk_fma_f32 v[84:85], v[192:193], s[34:35], v[84:85] op_sel_hi:[1,0,1]
	v_pk_fma_f32 v[54:55], v[190:191], s[34:35], v[54:55] op_sel_hi:[1,0,1]
	v_pk_fma_f32 v[52:53], v[188:189], s[34:35], v[52:53] op_sel_hi:[1,0,1]
	v_pk_fma_f32 v[34:35], v[186:187], s[34:35], v[34:35] op_sel_hi:[1,0,1]
	v_pk_fma_f32 v[32:33], v[184:185], s[34:35], v[32:33] op_sel_hi:[1,0,1]
	v_pk_fma_f32 v[18:19], v[182:183], s[34:35], v[18:19] op_sel_hi:[1,0,1]
	v_pk_fma_f32 v[16:17], v[180:181], s[34:35], v[16:17] op_sel_hi:[1,0,1]
	s_nop 0
	global_load_dwordx4 v[132:135], v[156:157], off offset:64
	global_load_dwordx4 v[176:179], v[138:139], off
	global_load_dwordx4 v[180:183], v[130:131], off offset:512 nt
	global_load_dwordx4 v[184:187], v[128:129], off offset:512 nt
	global_load_dwordx4 v[188:191], v[136:137], off offset:512 nt
	global_load_dwordx4 v[192:195], v[140:141], off offset:512 nt
	v_or_b32_e32 v138, 0x80, v166
	v_ashrrev_i32_e32 v139, 31, v138
	v_lshl_add_u64 v[138:139], v[138:139], 2, s[0:1]
	v_or_b32_e32 v166, 0x90, v166
	v_ashrrev_i32_e32 v167, 31, v166
	s_waitcnt vmcnt(5)
	v_pk_add_f32 v[70:71], v[70:71], v[134:135]
	v_pk_add_f32 v[68:69], v[68:69], v[132:133]
	v_pk_add_f32 v[50:51], v[50:51], v[134:135]
	v_pk_add_f32 v[48:49], v[48:49], v[132:133]
	v_pk_add_f32 v[26:27], v[26:27], v[134:135]
	v_pk_add_f32 v[24:25], v[24:25], v[132:133]
	v_pk_add_f32 v[10:11], v[10:11], v[134:135]
	v_pk_add_f32 v[8:9], v[8:9], v[132:133]
	s_waitcnt vmcnt(4)
	v_pk_mul_f32 v[70:71], v[178:179], v[70:71]
	v_pk_mul_f32 v[68:69], v[176:177], v[68:69]
	v_pk_mul_f32 v[50:51], v[178:179], v[50:51]
	v_pk_mul_f32 v[48:49], v[176:177], v[48:49]
	v_pk_mul_f32 v[26:27], v[178:179], v[26:27]
	v_pk_mul_f32 v[24:25], v[176:177], v[24:25]
	v_pk_mul_f32 v[10:11], v[178:179], v[10:11]
	v_pk_mul_f32 v[8:9], v[176:177], v[8:9]
	v_pk_fma_f32 v[70:71], v[210:211], s[34:35], v[70:71] op_sel_hi:[1,0,1]
	v_pk_fma_f32 v[68:69], v[208:209], s[34:35], v[68:69] op_sel_hi:[1,0,1]
	v_pk_fma_f32 v[50:51], v[206:207], s[34:35], v[50:51] op_sel_hi:[1,0,1]
	v_pk_fma_f32 v[48:49], v[204:205], s[34:35], v[48:49] op_sel_hi:[1,0,1]
	v_pk_fma_f32 v[26:27], v[202:203], s[34:35], v[26:27] op_sel_hi:[1,0,1]
	v_pk_fma_f32 v[24:25], v[200:201], s[34:35], v[24:25] op_sel_hi:[1,0,1]
	v_pk_fma_f32 v[10:11], v[198:199], s[34:35], v[10:11] op_sel_hi:[1,0,1]
	v_pk_fma_f32 v[8:9], v[196:197], s[34:35], v[8:9] op_sel_hi:[1,0,1]
	s_nop 0
	global_load_dwordx4 v[132:135], v[156:157], off offset:512
	global_load_dwordx4 v[176:179], v[138:139], off
	global_load_dwordx4 v[196:199], v[158:159], off offset:512 nt
	global_load_dwordx4 v[200:203], v[160:161], off offset:512 nt
	global_load_dwordx4 v[204:207], v[162:163], off offset:512 nt
	global_load_dwordx4 v[208:211], v[164:165], off offset:512 nt
	s_waitcnt vmcnt(5)
	v_pk_add_f32 v[74:75], v[74:75], v[134:135]
	v_pk_add_f32 v[72:73], v[72:73], v[132:133]
	v_pk_add_f32 v[42:43], v[42:43], v[134:135]
	v_pk_add_f32 v[40:41], v[40:41], v[132:133]
	v_pk_add_f32 v[22:23], v[22:23], v[134:135]
	v_pk_add_f32 v[20:21], v[20:21], v[132:133]
	v_pk_add_f32 v[6:7], v[6:7], v[134:135]
	v_pk_add_f32 v[4:5], v[4:5], v[132:133]
	s_waitcnt vmcnt(4)
	v_pk_mul_f32 v[74:75], v[178:179], v[74:75]
	v_pk_mul_f32 v[72:73], v[176:177], v[72:73]
	v_pk_mul_f32 v[42:43], v[178:179], v[42:43]
	v_pk_mul_f32 v[40:41], v[176:177], v[40:41]
	v_pk_mul_f32 v[22:23], v[178:179], v[22:23]
	v_pk_mul_f32 v[20:21], v[176:177], v[20:21]
	v_pk_mul_f32 v[6:7], v[178:179], v[6:7]
	v_pk_mul_f32 v[4:5], v[176:177], v[4:5]
	v_pk_fma_f32 v[74:75], v[194:195], s[34:35], v[74:75] op_sel_hi:[1,0,1]
	v_pk_fma_f32 v[72:73], v[192:193], s[34:35], v[72:73] op_sel_hi:[1,0,1]
	v_pk_fma_f32 v[42:43], v[190:191], s[34:35], v[42:43] op_sel_hi:[1,0,1]
	v_pk_fma_f32 v[40:41], v[188:189], s[34:35], v[40:41] op_sel_hi:[1,0,1]
	v_pk_fma_f32 v[22:23], v[186:187], s[34:35], v[22:23] op_sel_hi:[1,0,1]
	v_pk_fma_f32 v[20:21], v[184:185], s[34:35], v[20:21] op_sel_hi:[1,0,1]
	v_pk_fma_f32 v[6:7], v[182:183], s[34:35], v[6:7] op_sel_hi:[1,0,1]
	v_pk_fma_f32 v[4:5], v[180:181], s[34:35], v[4:5] op_sel_hi:[1,0,1]
	v_lshl_add_u64 v[192:193], v[166:167], 2, s[0:1]
	global_load_dwordx4 v[176:179], v[156:157], off offset:512
	global_load_dwordx4 v[180:183], v[138:139], off
	global_load_dwordx4 v[132:135], v[128:129], off offset:576 nt
	s_nop 0
	global_load_dwordx4 v[128:131], v[130:131], off offset:576 nt
	s_nop 0
	global_load_dwordx4 v[136:139], v[136:137], off offset:576 nt
	s_nop 0
	global_load_dwordx4 v[140:143], v[140:141], off offset:576 nt
	v_and_b32_e32 v166, 64, v172
	v_mov_b32_e32 v194, v81
	v_mov_b32_e32 v195, v82
	s_lshl_b32 s0, s39, 3
	s_add_i32 s7, s0, 0
	s_waitcnt vmcnt(5)
;     __device__ __forceinline__ bool run(const f32x4 (&v)[2][2][4][2], const Unit& u, int wr, int wc, int fr, int fq, PG8_LAS unsigned char* lds, int wid, int lane) const {
;     ...
;                     for (int n = 0; n < 2; ++n) { const f32x4 x = v[ai][bj][m][n]; s += (x[0] + x[1]) + (x[2] + x[3]); }
;                 s += __shfl_xor(s, 16); s += __shfl_xor(s, 32);
;                 const float mw = s * (1.0f / 64.0f); float q = 0.f;
; #pragma unroll
;                 for (int bj = 0; bj < 2; ++bj)
; #pragma unroll
;                     for (int n = 0; n < 2; ++n) { const f32x4 d = v[ai][bj][m][n] - mw; q += (d[0] * d[0] + d[1] * d[1]) + (d[2] * d[2] + d[3] * d[3]); }
;                 q += __shfl_xor(q, 16); q += __shfl_xor(q, 32);
;     __device__ __forceinline__ void fused(f32x4 (&acc)[2][2][4][2], const Unit& u, int wr, int wc, int fr, int fq, PG8_LAS unsigned char* lds, int wid, int lane) const {
;     ...
;             for (int m = 0; m < 4; ++m) acc[ai][bj][m][n] = xc[m] * ALPHA + gv * (acc[ai][bj][m][n] + bv);
;             asm volatile("" : "+v"(acc[ai][bj][0][n]), "+v"(acc[ai][bj][1][n]), "+v"(acc[ai][bj][2][n]), "+v"(acc[ai][bj][3][n]));
;             asm volatile("" ::: "memory");
; #pragma unroll
;             for (int m = 0; m < 4; ++m) xc[m] = xn[m]; }
	v_pk_add_f32 v[58:59], v[58:59], v[178:179]
	v_pk_add_f32 v[56:57], v[56:57], v[176:177]
	v_pk_add_f32 v[38:39], v[38:39], v[178:179]
	v_pk_add_f32 v[36:37], v[36:37], v[176:177]
	v_pk_add_f32 v[14:15], v[14:15], v[178:179]
	v_pk_add_f32 v[12:13], v[12:13], v[176:177]
	v_pk_add_f32 v[2:3], v[2:3], v[178:179]
	v_pk_add_f32 v[0:1], v[0:1], v[176:177]
	s_waitcnt vmcnt(4)
	v_pk_mul_f32 v[58:59], v[182:183], v[58:59]
	v_pk_mul_f32 v[56:57], v[180:181], v[56:57]
	v_pk_mul_f32 v[38:39], v[182:183], v[38:39]
	v_pk_mul_f32 v[36:37], v[180:181], v[36:37]
	v_pk_mul_f32 v[14:15], v[182:183], v[14:15]
	v_pk_mul_f32 v[12:13], v[180:181], v[12:13]
	v_pk_mul_f32 v[2:3], v[182:183], v[2:3]
	v_pk_mul_f32 v[0:1], v[180:181], v[0:1]
	v_pk_fma_f32 v[58:59], v[210:211], s[34:35], v[58:59] op_sel_hi:[1,0,1]
	v_pk_fma_f32 v[56:57], v[208:209], s[34:35], v[56:57] op_sel_hi:[1,0,1]
	v_pk_fma_f32 v[38:39], v[206:207], s[34:35], v[38:39] op_sel_hi:[1,0,1]
	v_pk_fma_f32 v[36:37], v[204:205], s[34:35], v[36:37] op_sel_hi:[1,0,1]
	v_pk_fma_f32 v[14:15], v[202:203], s[34:35], v[14:15] op_sel_hi:[1,0,1]
	v_pk_fma_f32 v[12:13], v[200:201], s[34:35], v[12:13] op_sel_hi:[1,0,1]
	v_pk_fma_f32 v[2:3], v[198:199], s[34:35], v[2:3] op_sel_hi:[1,0,1]
	v_pk_fma_f32 v[0:1], v[196:197], s[34:35], v[0:1] op_sel_hi:[1,0,1]
	v_add_u32_e32 v198, 64, v166
	global_load_dwordx4 v[176:179], v[156:157], off offset:576
	global_load_dwordx4 v[180:183], v[192:193], off
	s_nop 0
	global_load_dwordx4 v[164:167], v[164:165], off offset:576 nt
	s_nop 0
	global_load_dwordx4 v[184:187], v[162:163], off offset:576 nt
	s_nop 0
	global_load_dwordx4 v[160:163], v[160:161], off offset:576 nt
	s_nop 0
	global_load_dwordx4 v[188:191], v[158:159], off offset:576 nt
	v_mov_b32_e32 v196, v80
	v_mov_b32_e32 v197, v83
	v_cmp_lt_i32_e32 vcc, v148, v198
	s_waitcnt vmcnt(5)
	v_pk_add_f32 v[118:119], v[118:119], v[178:179]
	v_pk_add_f32 v[116:117], v[116:117], v[176:177]
	v_pk_add_f32 v[110:111], v[110:111], v[178:179]
	v_pk_add_f32 v[108:109], v[108:109], v[176:177]
	v_pk_add_f32 v[102:103], v[102:103], v[178:179]
	v_pk_add_f32 v[100:101], v[100:101], v[176:177]
	v_pk_add_f32 v[98:99], v[98:99], v[178:179]
	v_pk_add_f32 v[96:97], v[96:97], v[176:177]
	s_waitcnt vmcnt(4)
	v_pk_mul_f32 v[118:119], v[182:183], v[118:119]
	v_pk_mul_f32 v[116:117], v[180:181], v[116:117]
	v_pk_mul_f32 v[110:111], v[182:183], v[110:111]
	v_pk_mul_f32 v[108:109], v[180:181], v[108:109]
	v_pk_mul_f32 v[102:103], v[182:183], v[102:103]
	v_pk_mul_f32 v[100:101], v[180:181], v[100:101]
	v_pk_mul_f32 v[98:99], v[182:183], v[98:99]
	v_pk_mul_f32 v[96:97], v[180:181], v[96:97]
	v_pk_fma_f32 v[118:119], v[142:143], s[34:35], v[118:119] op_sel_hi:[1,0,1]
	v_pk_fma_f32 v[116:117], v[140:141], s[34:35], v[116:117] op_sel_hi:[1,0,1]
	v_pk_fma_f32 v[110:111], v[138:139], s[34:35], v[110:111] op_sel_hi:[1,0,1]
	v_pk_fma_f32 v[108:109], v[136:137], s[34:35], v[108:109] op_sel_hi:[1,0,1]
	v_pk_fma_f32 v[102:103], v[134:135], s[34:35], v[102:103] op_sel_hi:[1,0,1]
	v_pk_fma_f32 v[100:101], v[132:133], s[34:35], v[100:101] op_sel_hi:[1,0,1]
	v_pk_fma_f32 v[98:99], v[130:131], s[34:35], v[98:99] op_sel_hi:[1,0,1]
	v_pk_fma_f32 v[96:97], v[128:129], s[34:35], v[96:97] op_sel_hi:[1,0,1]
	v_mov_b32_e32 v130, v85
	global_load_dwordx4 v[134:137], v[156:157], off offset:576
	global_load_dwordx4 v[138:141], v[192:193], off
	v_mov_b32_e32 v131, v86
	v_mov_b32_e32 v132, v84
	v_mov_b32_e32 v133, v87
	v_pk_add_f32 v[128:129], v[194:195], v[196:197]
	v_pk_add_f32 v[130:131], v[130:131], v[132:133]
	v_add_f32_e32 v128, v128, v129
	v_pk_add_f32 v[130:131], v[130:131], v[130:131] op_sel:[0,1] op_sel_hi:[1,0]
	v_add_f32_e32 v128, 0, v128
	v_add_f32_e32 v132, v72, v73
	v_add_f32_e32 v142, v74, v75
	v_mov_b32_e32 v129, v116
	v_mov_b32_e32 v131, v117
	v_mov_b32_e32 v133, v118
	v_mov_b32_e32 v143, v119
	v_pk_add_f32 v[128:129], v[128:129], v[130:131]
	v_pk_add_f32 v[130:131], v[132:133], v[142:143]
	v_cndmask_b32_e32 v148, v172, v148, vcc
	v_pk_add_f32 v[128:129], v[128:129], v[130:131]
	v_lshlrev_b32_e32 v148, 2, v148
	v_add_f32_e32 v129, v128, v129
	v_mov_b32_e32 v130, v129
	v_mov_b32_e32 v212, v129
	s_nop 1
	v_permlane16_swap_b32_e32 v130, v212
	v_xor_b32_e32 v128, 32, v172
	v_cmp_lt_i32_e32 vcc, v128, v198
	s_waitcnt lgkmcnt(0)
	v_add_f32_e32 v129, v130, v212
	v_cndmask_b32_e32 v128, v172, v128, vcc
	v_lshlrev_b32_e32 v128, 2, v128
	v_mov_b32_e32 v130, v129
	v_mov_b32_e32 v212, v129
	s_nop 1
	v_permlane32_swap_b32_e32 v130, v212
	s_waitcnt lgkmcnt(0)
	v_add_f32_e32 v129, v130, v212
	v_fmamk_f32 v131, v129, 0xbc800000, v83
	v_fmamk_f32 v133, v129, 0xbc800000, v81
	v_fmamk_f32 v143, v129, 0xbc800000, v87
	v_fmamk_f32 v157, v129, 0xbc800000, v85
	v_fmamk_f32 v130, v129, 0xbc800000, v82
	v_fmamk_f32 v132, v129, 0xbc800000, v80
	v_fmamk_f32 v142, v129, 0xbc800000, v86
	v_fmamk_f32 v156, v129, 0xbc800000, v84
	v_fmamk_f32 v159, v129, 0xbc800000, v75
	v_fmamk_f32 v177, v129, 0xbc800000, v73
	v_mul_f32_e32 v133, v133, v133
	v_mul_f32_e32 v131, v131, v131
	v_mul_f32_e32 v157, v157, v157
	v_mul_f32_e32 v143, v143, v143
	v_fmamk_f32 v158, v129, 0xbc800000, v74
	v_fmamk_f32 v176, v129, 0xbc800000, v72
	v_fmamk_f32 v179, v129, 0xbc800000, v119
	v_fmamk_f32 v181, v129, 0xbc800000, v117
	v_mul_f32_e32 v177, v177, v177
	v_mul_f32_e32 v159, v159, v159
	v_fmac_f32_e32 v133, v132, v132
	v_fmac_f32_e32 v131, v130, v130
	v_fmac_f32_e32 v157, v156, v156
	v_fmac_f32_e32 v143, v142, v142
	v_fmamk_f32 v178, v129, 0xbc800000, v118
	v_fmamk_f32 v180, v129, 0xbc800000, v116
	v_mul_f32_e32 v181, v181, v181
	v_mul_f32_e32 v179, v179, v179
	v_fmac_f32_e32 v177, v176, v176
	v_fmac_f32_e32 v159, v158, v158
	v_add_f32_e32 v130, v133, v131
	v_add_f32_e32 v131, v157, v143
	v_fmac_f32_e32 v181, v180, v180
	v_fmac_f32_e32 v179, v178, v178
	v_add_f32_e32 v132, v177, v159
	v_add_f32_e32 v130, v130, v131
	v_add_f32_e32 v133, v181, v179
	v_add_f32_e32 v130, v132, v130
	v_add_f32_e32 v131, v133, v130
	v_mov_b32_e32 v132, v131
	v_mov_b32_e32 v212, v131
	s_nop 1
	v_permlane16_swap_b32_e32 v132, v212
	v_and_b32_e32 v130, 63, v174
	v_cmp_gt_u32_e32 vcc, 16, v130
	s_waitcnt lgkmcnt(0)
;     __device__ __forceinline__ bool run(const f32x4 (&v)[2][2][4][2], const Unit& u, int wr, int wc, int fr, int fq, PG8_LAS unsigned char* lds, int wid, int lane) const {
;     ...
;                     for (int n = 0; n < 2; ++n) { const f32x4 x = v[ai][bj][m][n]; s += (x[0] + x[1]) + (x[2] + x[3]); }
;                 s += __shfl_xor(s, 16); s += __shfl_xor(s, 32);
;                 const float mw = s * (1.0f / 64.0f); float q = 0.f;
; #pragma unroll
;                 for (int bj = 0; bj < 2; ++bj)
; #pragma unroll
;                     for (int n = 0; n < 2; ++n) { const f32x4 d = v[ai][bj][m][n] - mw; q += (d[0] * d[0] + d[1] * d[1]) + (d[2] * d[2] + d[3] * d[3]); }
;                 q += __shfl_xor(q, 16); q += __shfl_xor(q, 32);
;                 if (fq == 0) P[(ai * HALF + wr * 64 + m * 16 + fr) * 4 + wc] = (f32x2v){mw, q};
;     __device__ __forceinline__ void fused(f32x4 (&acc)[2][2][4][2], const Unit& u, int wr, int wc, int fr, int fq, PG8_LAS unsigned char* lds, int wid, int lane) const {
;     ...
;             for (int m = 0; m < 4; ++m) acc[ai][bj][m][n] = xc[m] * ALPHA + gv * (acc[ai][bj][m][n] + bv);
;             asm volatile("" : "+v"(acc[ai][bj][0][n]), "+v"(acc[ai][bj][1][n]), "+v"(acc[ai][bj][2][n]), "+v"(acc[ai][bj][3][n]));
	v_add_f32_e32 v131, v132, v212
	s_waitcnt vmcnt(1)
	v_pk_add_f32 v[126:127], v[126:127], v[136:137]
	v_pk_add_f32 v[124:125], v[124:125], v[134:135]
	v_pk_add_f32 v[122:123], v[122:123], v[136:137]
	v_pk_add_f32 v[120:121], v[120:121], v[134:135]
	v_pk_add_f32 v[114:115], v[114:115], v[136:137]
	v_pk_add_f32 v[112:113], v[112:113], v[134:135]
	v_pk_add_f32 v[106:107], v[106:107], v[136:137]
	v_pk_add_f32 v[104:105], v[104:105], v[134:135]
	v_mov_b32_e32 v132, v131
	v_mov_b32_e32 v212, v131
	s_nop 1
	v_permlane32_swap_b32_e32 v132, v212
	s_waitcnt vmcnt(0)
	v_pk_mul_f32 v[126:127], v[140:141], v[126:127]
	v_pk_mul_f32 v[124:125], v[138:139], v[124:125]
	v_pk_mul_f32 v[122:123], v[140:141], v[122:123]
	v_pk_mul_f32 v[120:121], v[138:139], v[120:121]
	v_pk_mul_f32 v[114:115], v[140:141], v[114:115]
	v_pk_mul_f32 v[112:113], v[138:139], v[112:113]
	v_pk_mul_f32 v[106:107], v[140:141], v[106:107]
	v_pk_mul_f32 v[104:105], v[138:139], v[104:105]
	v_pk_fma_f32 v[126:127], v[166:167], s[34:35], v[126:127] op_sel_hi:[1,0,1]
	v_pk_fma_f32 v[124:125], v[164:165], s[34:35], v[124:125] op_sel_hi:[1,0,1]
	v_pk_fma_f32 v[122:123], v[186:187], s[34:35], v[122:123] op_sel_hi:[1,0,1]
	v_pk_fma_f32 v[120:121], v[184:185], s[34:35], v[120:121] op_sel_hi:[1,0,1]
	v_pk_fma_f32 v[114:115], v[162:163], s[34:35], v[114:115] op_sel_hi:[1,0,1]
	v_pk_fma_f32 v[112:113], v[160:161], s[34:35], v[112:113] op_sel_hi:[1,0,1]
	v_pk_fma_f32 v[106:107], v[190:191], s[34:35], v[106:107] op_sel_hi:[1,0,1]
	v_pk_fma_f32 v[104:105], v[188:189], s[34:35], v[104:105] op_sel_hi:[1,0,1]
	s_nop 0
	s_and_saveexec_b64 s[0:1], vcc
	s_cbranch_execz .LBB0_498
	s_lshl_b32 s39, s59, 11
	s_add_i32 s39, s7, s39
	v_mul_f32_e32 v134, 0x3c800000, v129
	v_lshl_add_u32 v129, v175, 5, s39
	s_waitcnt lgkmcnt(0)
	v_add_f32_e32 v135, v132, v212
	ds_write_b64 v129, v[134:135]
.LBB0_498:
	s_or_b64 exec, exec, s[0:1]
	s_waitcnt lgkmcnt(0)
	v_mov_b32_e32 v132, v77
	v_mov_b32_e32 v133, v78
	v_mov_b32_e32 v134, v76
	v_mov_b32_e32 v135, v79
	v_pk_add_f32 v[132:133], v[132:133], v[134:135]
	v_mov_b32_e32 v134, v53
	v_mov_b32_e32 v135, v54
	v_mov_b32_e32 v136, v52
	v_mov_b32_e32 v137, v55
	v_pk_add_f32 v[134:135], v[134:135], v[136:137]
	v_add_f32_e32 v129, v132, v133
	v_pk_add_f32 v[134:135], v[134:135], v[134:135] op_sel:[0,1] op_sel_hi:[1,0]
	v_add_f32_e32 v132, 0, v129
	v_add_f32_e32 v136, v40, v41
	v_add_f32_e32 v138, v42, v43
	v_mov_b32_e32 v133, v108
	v_mov_b32_e32 v135, v109
	v_mov_b32_e32 v137, v110
	v_mov_b32_e32 v139, v111
	v_pk_add_f32 v[132:133], v[132:133], v[134:135]
	v_pk_add_f32 v[134:135], v[136:137], v[138:139]
	s_nop 0
	v_pk_add_f32 v[132:133], v[132:133], v[134:135]
	s_nop 0
	v_add_f32_e32 v129, v132, v133
	v_mov_b32_e32 v131, v129
	v_mov_b32_e32 v212, v129
	s_nop 1
	v_permlane16_swap_b32_e32 v131, v212
	s_waitcnt lgkmcnt(0)
	v_add_f32_e32 v129, v131, v212
	v_mov_b32_e32 v131, v129
	v_mov_b32_e32 v212, v129
	s_nop 1
	v_permlane32_swap_b32_e32 v131, v212
	s_waitcnt lgkmcnt(0)
	v_add_f32_e32 v129, v131, v212
	v_fmamk_f32 v132, v129, 0xbc800000, v79
	v_fmamk_f32 v134, v129, 0xbc800000, v77
	v_fmamk_f32 v131, v129, 0xbc800000, v78
	v_fmamk_f32 v133, v129, 0xbc800000, v76
	v_mul_f32_e32 v134, v134, v134
	v_mul_f32_e32 v132, v132, v132
	v_fmac_f32_e32 v134, v133, v133
	v_fmac_f32_e32 v132, v131, v131
	v_fmamk_f32 v133, v129, 0xbc800000, v55
	v_fmamk_f32 v135, v129, 0xbc800000, v53
	v_add_f32_e32 v131, v134, v132
	v_fmamk_f32 v132, v129, 0xbc800000, v54
	v_fmamk_f32 v134, v129, 0xbc800000, v52
	v_mul_f32_e32 v135, v135, v135
	v_mul_f32_e32 v133, v133, v133
	v_fmac_f32_e32 v135, v134, v134
	v_fmac_f32_e32 v133, v132, v132
	v_add_f32_e32 v132, v135, v133
	v_fmamk_f32 v133, v129, 0xbc800000, v43
	v_fmamk_f32 v135, v129, 0xbc800000, v41
	v_add_f32_e32 v131, v131, v132
	v_fmamk_f32 v132, v129, 0xbc800000, v42
	v_fmamk_f32 v134, v129, 0xbc800000, v40
	v_mul_f32_e32 v135, v135, v135
	v_mul_f32_e32 v133, v133, v133
	v_fmac_f32_e32 v135, v134, v134
	v_fmac_f32_e32 v133, v132, v132
	v_add_f32_e32 v132, v135, v133
	v_fmamk_f32 v133, v129, 0xbc800000, v111
	v_fmamk_f32 v135, v129, 0xbc800000, v109
	v_add_f32_e32 v131, v132, v131
	v_fmamk_f32 v132, v129, 0xbc800000, v110
	v_fmamk_f32 v134, v129, 0xbc800000, v108
	v_mul_f32_e32 v135, v135, v135
	v_mul_f32_e32 v133, v133, v133
	v_fmac_f32_e32 v135, v134, v134
	v_fmac_f32_e32 v133, v132, v132
	v_add_f32_e32 v132, v135, v133
	v_add_f32_e32 v131, v132, v131
	v_mov_b32_e32 v132, v131
	v_mov_b32_e32 v212, v131
	s_nop 1
	v_permlane16_swap_b32_e32 v132, v212
	s_waitcnt lgkmcnt(0)
	v_add_f32_e32 v131, v132, v212
	v_mov_b32_e32 v132, v131
	v_mov_b32_e32 v212, v131
	s_nop 1
	v_permlane32_swap_b32_e32 v132, v212
	s_and_saveexec_b64 s[0:1], vcc
	s_cbranch_execz .LBB0_500
	s_lshl_b32 s39, s59, 11
	s_add_i32 s39, s7, s39
	v_mul_f32_e32 v134, 0x3c800000, v129
	v_lshl_add_u32 v129, v175, 5, s39
	s_waitcnt lgkmcnt(0)
	v_add_f32_e32 v135, v132, v212
	ds_write_b64 v129, v[134:135] offset:512
;     __device__ __forceinline__ bool run(const f32x4 (&v)[2][2][4][2], const Unit& u, int wr, int wc, int fr, int fq, PG8_LAS unsigned char* lds, int wid, int lane) const {
;     ...
;                     for (int n = 0; n < 2; ++n) { const f32x4 x = v[ai][bj][m][n]; s += (x[0] + x[1]) + (x[2] + x[3]); }
;                 s += __shfl_xor(s, 16); s += __shfl_xor(s, 32);
;                 const float mw = s * (1.0f / 64.0f); float q = 0.f;
; #pragma unroll
;                 for (int bj = 0; bj < 2; ++bj)
; #pragma unroll
;                     for (int n = 0; n < 2; ++n) { const f32x4 d = v[ai][bj][m][n] - mw; q += (d[0] * d[0] + d[1] * d[1]) + (d[2] * d[2] + d[3] * d[3]); }
;                 q += __shfl_xor(q, 16); q += __shfl_xor(q, 32);
;                 if (fq == 0) P[(ai * HALF + wr * 64 + m * 16 + fr) * 4 + wc] = (f32x2v){mw, q};
.LBB0_500:
	s_or_b64 exec, exec, s[0:1]
	s_waitcnt lgkmcnt(0)
	v_mov_b32_e32 v132, v61
	v_mov_b32_e32 v133, v62
	v_mov_b32_e32 v134, v60
	v_mov_b32_e32 v135, v63
	v_pk_add_f32 v[132:133], v[132:133], v[134:135]
	v_mov_b32_e32 v134, v33
	v_mov_b32_e32 v135, v34
	v_mov_b32_e32 v136, v32
	v_mov_b32_e32 v137, v35
	v_pk_add_f32 v[134:135], v[134:135], v[136:137]
	v_add_f32_e32 v129, v132, v133
	v_pk_add_f32 v[134:135], v[134:135], v[134:135] op_sel:[0,1] op_sel_hi:[1,0]
	v_add_f32_e32 v132, 0, v129
	v_add_f32_e32 v136, v20, v21
	v_add_f32_e32 v138, v22, v23
	v_mov_b32_e32 v133, v100
	v_mov_b32_e32 v135, v101
	v_mov_b32_e32 v137, v102
	v_mov_b32_e32 v139, v103
	v_pk_add_f32 v[132:133], v[132:133], v[134:135]
	v_pk_add_f32 v[134:135], v[136:137], v[138:139]
	s_nop 0
	v_pk_add_f32 v[132:133], v[132:133], v[134:135]
	s_nop 0
	v_add_f32_e32 v129, v132, v133
	v_mov_b32_e32 v131, v129
	v_mov_b32_e32 v212, v129
	s_nop 1
	v_permlane16_swap_b32_e32 v131, v212
	s_waitcnt lgkmcnt(0)
	v_add_f32_e32 v129, v131, v212
	v_mov_b32_e32 v131, v129
	v_mov_b32_e32 v212, v129
	s_nop 1
	v_permlane32_swap_b32_e32 v131, v212
	s_waitcnt lgkmcnt(0)
	v_add_f32_e32 v129, v131, v212
	v_fmamk_f32 v132, v129, 0xbc800000, v63
	v_fmamk_f32 v134, v129, 0xbc800000, v61
	v_fmamk_f32 v131, v129, 0xbc800000, v62
	v_fmamk_f32 v133, v129, 0xbc800000, v60
	v_mul_f32_e32 v134, v134, v134
	v_mul_f32_e32 v132, v132, v132
	v_fmac_f32_e32 v134, v133, v133
	v_fmac_f32_e32 v132, v131, v131
	v_fmamk_f32 v133, v129, 0xbc800000, v35
	v_fmamk_f32 v135, v129, 0xbc800000, v33
	v_add_f32_e32 v131, v134, v132
	v_fmamk_f32 v132, v129, 0xbc800000, v34
	v_fmamk_f32 v134, v129, 0xbc800000, v32
	v_mul_f32_e32 v135, v135, v135
	v_mul_f32_e32 v133, v133, v133
	v_fmac_f32_e32 v135, v134, v134
	v_fmac_f32_e32 v133, v132, v132
	v_add_f32_e32 v132, v135, v133
	v_fmamk_f32 v133, v129, 0xbc800000, v23
	v_fmamk_f32 v135, v129, 0xbc800000, v21
	v_add_f32_e32 v131, v131, v132
	v_fmamk_f32 v132, v129, 0xbc800000, v22
	v_fmamk_f32 v134, v129, 0xbc800000, v20
	v_mul_f32_e32 v135, v135, v135
	v_mul_f32_e32 v133, v133, v133
	v_fmac_f32_e32 v135, v134, v134
	v_fmac_f32_e32 v133, v132, v132
	v_add_f32_e32 v132, v135, v133
	v_fmamk_f32 v133, v129, 0xbc800000, v103
	v_fmamk_f32 v135, v129, 0xbc800000, v101
	v_add_f32_e32 v131, v132, v131
	v_fmamk_f32 v132, v129, 0xbc800000, v102
	v_fmamk_f32 v134, v129, 0xbc800000, v100
	v_mul_f32_e32 v135, v135, v135
	v_mul_f32_e32 v133, v133, v133
	v_fmac_f32_e32 v135, v134, v134
	v_fmac_f32_e32 v133, v132, v132
	v_add_f32_e32 v132, v135, v133
	v_add_f32_e32 v131, v132, v131
	v_mov_b32_e32 v132, v131
	v_mov_b32_e32 v212, v131
	s_nop 1
	v_permlane16_swap_b32_e32 v132, v212
	s_waitcnt lgkmcnt(0)
	v_add_f32_e32 v131, v132, v212
	v_mov_b32_e32 v132, v131
	v_mov_b32_e32 v212, v131
	s_nop 1
	v_permlane32_swap_b32_e32 v132, v212
	s_and_saveexec_b64 s[0:1], vcc
	s_cbranch_execz .LBB0_502
	s_lshl_b32 s39, s59, 11
	s_add_i32 s39, s7, s39
	v_mul_f32_e32 v134, 0x3c800000, v129
	v_lshl_add_u32 v129, v175, 5, s39
	s_waitcnt lgkmcnt(0)
	v_add_f32_e32 v135, v132, v212
	ds_write_b64 v129, v[134:135] offset:1024
.LBB0_502:
	s_or_b64 exec, exec, s[0:1]
	s_waitcnt lgkmcnt(0)
	v_mov_b32_e32 v132, v65
	v_mov_b32_e32 v133, v66
	v_mov_b32_e32 v134, v64
	v_mov_b32_e32 v135, v67
	v_pk_add_f32 v[132:133], v[132:133], v[134:135]
	v_mov_b32_e32 v134, v17
	v_mov_b32_e32 v135, v18
	v_mov_b32_e32 v136, v16
	v_mov_b32_e32 v137, v19
	v_pk_add_f32 v[134:135], v[134:135], v[136:137]
	v_add_f32_e32 v129, v132, v133
	v_pk_add_f32 v[134:135], v[134:135], v[134:135] op_sel:[0,1] op_sel_hi:[1,0]
	v_add_f32_e32 v132, 0, v129
	v_add_f32_e32 v136, v4, v5
	v_add_f32_e32 v138, v6, v7
	v_mov_b32_e32 v133, v96
	v_mov_b32_e32 v135, v97
	v_mov_b32_e32 v137, v98
	v_mov_b32_e32 v139, v99
	v_pk_add_f32 v[132:133], v[132:133], v[134:135]
	v_pk_add_f32 v[134:135], v[136:137], v[138:139]
	s_nop 0
	v_pk_add_f32 v[132:133], v[132:133], v[134:135]
	s_nop 0
	v_add_f32_e32 v129, v132, v133
	v_mov_b32_e32 v131, v129
	v_mov_b32_e32 v212, v129
	s_nop 1
	v_permlane16_swap_b32_e32 v131, v212
	s_waitcnt lgkmcnt(0)
	v_add_f32_e32 v129, v131, v212
	v_mov_b32_e32 v131, v129
	v_mov_b32_e32 v212, v129
	s_nop 1
	v_permlane32_swap_b32_e32 v131, v212
	s_waitcnt lgkmcnt(0)
	v_add_f32_e32 v129, v131, v212
	v_fmamk_f32 v132, v129, 0xbc800000, v67
	v_fmamk_f32 v134, v129, 0xbc800000, v65
	v_fmamk_f32 v131, v129, 0xbc800000, v66
	v_fmamk_f32 v133, v129, 0xbc800000, v64
	v_mul_f32_e32 v134, v134, v134
	v_mul_f32_e32 v132, v132, v132
	v_fmac_f32_e32 v134, v133, v133
	v_fmac_f32_e32 v132, v131, v131
	v_fmamk_f32 v133, v129, 0xbc800000, v19
	v_fmamk_f32 v135, v129, 0xbc800000, v17
	v_add_f32_e32 v131, v134, v132
	v_fmamk_f32 v132, v129, 0xbc800000, v18
	v_fmamk_f32 v134, v129, 0xbc800000, v16
	v_mul_f32_e32 v135, v135, v135
	v_mul_f32_e32 v133, v133, v133
	v_fmac_f32_e32 v135, v134, v134
	v_fmac_f32_e32 v133, v132, v132
	v_add_f32_e32 v132, v135, v133
	v_fmamk_f32 v133, v129, 0xbc800000, v7
	v_fmamk_f32 v135, v129, 0xbc800000, v5
	v_add_f32_e32 v131, v131, v132
	v_fmamk_f32 v132, v129, 0xbc800000, v6
	v_fmamk_f32 v134, v129, 0xbc800000, v4
	v_mul_f32_e32 v135, v135, v135
	v_mul_f32_e32 v133, v133, v133
	v_fmac_f32_e32 v135, v134, v134
	v_fmac_f32_e32 v133, v132, v132
	v_add_f32_e32 v132, v135, v133
	v_fmamk_f32 v133, v129, 0xbc800000, v99
	v_fmamk_f32 v135, v129, 0xbc800000, v97
	v_add_f32_e32 v131, v132, v131
	v_fmamk_f32 v132, v129, 0xbc800000, v98
	v_fmamk_f32 v134, v129, 0xbc800000, v96
	v_mul_f32_e32 v135, v135, v135
	v_mul_f32_e32 v133, v133, v133
	v_fmac_f32_e32 v135, v134, v134
	v_fmac_f32_e32 v133, v132, v132
	v_add_f32_e32 v132, v135, v133
	v_add_f32_e32 v131, v132, v131
	v_mov_b32_e32 v132, v131
	v_mov_b32_e32 v212, v131
	s_nop 1
	v_permlane16_swap_b32_e32 v132, v212
	s_waitcnt lgkmcnt(0)
	v_add_f32_e32 v131, v132, v212
	v_mov_b32_e32 v132, v131
	v_mov_b32_e32 v212, v131
	s_nop 1
	v_permlane32_swap_b32_e32 v132, v212
	s_and_saveexec_b64 s[0:1], vcc
	s_cbranch_execz .LBB0_504
	s_lshl_b32 s39, s59, 11
	s_add_i32 s39, s7, s39
	v_mul_f32_e32 v134, 0x3c800000, v129
	v_lshl_add_u32 v129, v175, 5, s39
	s_waitcnt lgkmcnt(0)
	v_add_f32_e32 v135, v132, v212
	ds_write_b64 v129, v[134:135] offset:1536
;     __device__ __forceinline__ bool run(const f32x4 (&v)[2][2][4][2], const Unit& u, int wr, int wc, int fr, int fq, PG8_LAS unsigned char* lds, int wid, int lane) const {
;     ...
;                     for (int n = 0; n < 2; ++n) { const f32x4 x = v[ai][bj][m][n]; s += (x[0] + x[1]) + (x[2] + x[3]); }
;                 s += __shfl_xor(s, 16); s += __shfl_xor(s, 32);
;                 const float mw = s * (1.0f / 64.0f); float q = 0.f;
; #pragma unroll
;                 for (int bj = 0; bj < 2; ++bj)
; #pragma unroll
;                     for (int n = 0; n < 2; ++n) { const f32x4 d = v[ai][bj][m][n] - mw; q += (d[0] * d[0] + d[1] * d[1]) + (d[2] * d[2] + d[3] * d[3]); }
;                 q += __shfl_xor(q, 16); q += __shfl_xor(q, 32);
;                 if (fq == 0) P[(ai * HALF + wr * 64 + m * 16 + fr) * 4 + wc] = (f32x2v){mw, q};
.LBB0_504:
	s_or_b64 exec, exec, s[0:1]
	s_waitcnt lgkmcnt(0)
	v_mov_b32_e32 v132, v93
	v_mov_b32_e32 v133, v94
	v_mov_b32_e32 v134, v92
	v_mov_b32_e32 v135, v95
	v_pk_add_f32 v[132:133], v[132:133], v[134:135]
	v_mov_b32_e32 v134, v69
	v_mov_b32_e32 v135, v70
	v_mov_b32_e32 v136, v68
	v_mov_b32_e32 v137, v71
	v_pk_add_f32 v[134:135], v[134:135], v[136:137]
	v_add_f32_e32 v129, v132, v133
	v_pk_add_f32 v[134:135], v[134:135], v[134:135] op_sel:[0,1] op_sel_hi:[1,0]
	v_add_f32_e32 v132, 0, v129
	v_add_f32_e32 v136, v56, v57
	v_add_f32_e32 v138, v58, v59
	v_mov_b32_e32 v133, v124
	v_mov_b32_e32 v135, v125
	v_mov_b32_e32 v137, v126
	v_mov_b32_e32 v139, v127
	v_pk_add_f32 v[132:133], v[132:133], v[134:135]
	v_pk_add_f32 v[134:135], v[136:137], v[138:139]
	s_nop 0
	v_pk_add_f32 v[132:133], v[132:133], v[134:135]
	s_nop 0
	v_add_f32_e32 v129, v132, v133
	v_mov_b32_e32 v131, v129
	v_mov_b32_e32 v212, v129
	s_nop 1
	v_permlane16_swap_b32_e32 v131, v212
	s_waitcnt lgkmcnt(0)
	v_add_f32_e32 v129, v131, v212
	v_mov_b32_e32 v131, v129
	v_mov_b32_e32 v212, v129
	s_nop 1
	v_permlane32_swap_b32_e32 v131, v212
	s_waitcnt lgkmcnt(0)
	v_add_f32_e32 v129, v131, v212
	v_fmamk_f32 v132, v129, 0xbc800000, v95
	v_fmamk_f32 v134, v129, 0xbc800000, v93
	v_fmamk_f32 v131, v129, 0xbc800000, v94
	v_fmamk_f32 v133, v129, 0xbc800000, v92
	v_mul_f32_e32 v134, v134, v134
	v_mul_f32_e32 v132, v132, v132
	v_fmac_f32_e32 v134, v133, v133
	v_fmac_f32_e32 v132, v131, v131
	v_fmamk_f32 v133, v129, 0xbc800000, v71
	v_fmamk_f32 v135, v129, 0xbc800000, v69
	v_add_f32_e32 v131, v134, v132
	v_fmamk_f32 v132, v129, 0xbc800000, v70
	v_fmamk_f32 v134, v129, 0xbc800000, v68
	v_mul_f32_e32 v135, v135, v135
	v_mul_f32_e32 v133, v133, v133
	v_fmac_f32_e32 v135, v134, v134
	v_fmac_f32_e32 v133, v132, v132
	v_add_f32_e32 v132, v135, v133
	v_fmamk_f32 v133, v129, 0xbc800000, v59
	v_fmamk_f32 v135, v129, 0xbc800000, v57
	v_add_f32_e32 v131, v131, v132
	v_fmamk_f32 v132, v129, 0xbc800000, v58
	v_fmamk_f32 v134, v129, 0xbc800000, v56
	v_mul_f32_e32 v135, v135, v135
	v_mul_f32_e32 v133, v133, v133
	v_fmac_f32_e32 v135, v134, v134
	v_fmac_f32_e32 v133, v132, v132
	v_add_f32_e32 v132, v135, v133
	v_fmamk_f32 v133, v129, 0xbc800000, v127
	v_fmamk_f32 v135, v129, 0xbc800000, v125
	v_add_f32_e32 v131, v132, v131
	v_fmamk_f32 v132, v129, 0xbc800000, v126
	v_fmamk_f32 v134, v129, 0xbc800000, v124
	v_mul_f32_e32 v135, v135, v135
	v_mul_f32_e32 v133, v133, v133
	v_fmac_f32_e32 v135, v134, v134
	v_fmac_f32_e32 v133, v132, v132
	v_add_f32_e32 v132, v135, v133
	v_add_f32_e32 v131, v132, v131
	v_mov_b32_e32 v132, v131
	v_mov_b32_e32 v212, v131
	s_nop 1
	v_permlane16_swap_b32_e32 v132, v212
	s_waitcnt lgkmcnt(0)
	v_add_f32_e32 v131, v132, v212
	v_mov_b32_e32 v132, v131
	v_mov_b32_e32 v212, v131
	s_nop 1
	v_permlane32_swap_b32_e32 v132, v212
	s_and_saveexec_b64 s[0:1], vcc
	s_cbranch_execz .LBB0_506
	s_lshl_b32 s39, s59, 11
	s_add_i32 s39, s7, s39
	v_mul_f32_e32 v134, 0x3c800000, v129
	v_lshl_add_u32 v129, v175, 5, s39
	s_waitcnt lgkmcnt(0)
	v_add_f32_e32 v135, v132, v212
	ds_write_b64 v129, v[134:135] offset:4096
.LBB0_506:
	s_or_b64 exec, exec, s[0:1]
	s_waitcnt lgkmcnt(0)
	v_mov_b32_e32 v132, v89
	v_mov_b32_e32 v133, v90
	v_mov_b32_e32 v134, v88
	v_mov_b32_e32 v135, v91
	v_pk_add_f32 v[132:133], v[132:133], v[134:135]
	v_mov_b32_e32 v134, v49
	v_mov_b32_e32 v135, v50
	v_mov_b32_e32 v136, v48
	v_mov_b32_e32 v137, v51
	v_pk_add_f32 v[134:135], v[134:135], v[136:137]
	v_add_f32_e32 v129, v132, v133
	v_pk_add_f32 v[134:135], v[134:135], v[134:135] op_sel:[0,1] op_sel_hi:[1,0]
	v_add_f32_e32 v132, 0, v129
	v_add_f32_e32 v136, v36, v37
	v_add_f32_e32 v138, v38, v39
	v_mov_b32_e32 v133, v120
	v_mov_b32_e32 v135, v121
	v_mov_b32_e32 v137, v122
	v_mov_b32_e32 v139, v123
	v_pk_add_f32 v[132:133], v[132:133], v[134:135]
	v_pk_add_f32 v[134:135], v[136:137], v[138:139]
	s_nop 0
	v_pk_add_f32 v[132:133], v[132:133], v[134:135]
	s_nop 0
	v_add_f32_e32 v129, v132, v133
	v_mov_b32_e32 v131, v129
	v_mov_b32_e32 v212, v129
	s_nop 1
	v_permlane16_swap_b32_e32 v131, v212
	s_waitcnt lgkmcnt(0)
	v_add_f32_e32 v129, v131, v212
	v_mov_b32_e32 v131, v129
	v_mov_b32_e32 v212, v129
	s_nop 1
	v_permlane32_swap_b32_e32 v131, v212
	s_waitcnt lgkmcnt(0)
	v_add_f32_e32 v129, v131, v212
	v_fmamk_f32 v132, v129, 0xbc800000, v91
	v_fmamk_f32 v134, v129, 0xbc800000, v89
	v_fmamk_f32 v131, v129, 0xbc800000, v90
	v_fmamk_f32 v133, v129, 0xbc800000, v88
	v_mul_f32_e32 v134, v134, v134
	v_mul_f32_e32 v132, v132, v132
	v_fmac_f32_e32 v134, v133, v133
	v_fmac_f32_e32 v132, v131, v131
	v_fmamk_f32 v133, v129, 0xbc800000, v51
	v_fmamk_f32 v135, v129, 0xbc800000, v49
	v_add_f32_e32 v131, v134, v132
	v_fmamk_f32 v132, v129, 0xbc800000, v50
	v_fmamk_f32 v134, v129, 0xbc800000, v48
	v_mul_f32_e32 v135, v135, v135
	v_mul_f32_e32 v133, v133, v133
	v_fmac_f32_e32 v135, v134, v134
	v_fmac_f32_e32 v133, v132, v132
	v_add_f32_e32 v132, v135, v133
	v_fmamk_f32 v133, v129, 0xbc800000, v39
	v_fmamk_f32 v135, v129, 0xbc800000, v37
	v_add_f32_e32 v131, v131, v132
	v_fmamk_f32 v132, v129, 0xbc800000, v38
	v_fmamk_f32 v134, v129, 0xbc800000, v36
	v_mul_f32_e32 v135, v135, v135
	v_mul_f32_e32 v133, v133, v133
	v_fmac_f32_e32 v135, v134, v134
	v_fmac_f32_e32 v133, v132, v132
	v_add_f32_e32 v132, v135, v133
	v_fmamk_f32 v133, v129, 0xbc800000, v123
	v_fmamk_f32 v135, v129, 0xbc800000, v121
	v_add_f32_e32 v131, v132, v131
	v_fmamk_f32 v132, v129, 0xbc800000, v122
	v_fmamk_f32 v134, v129, 0xbc800000, v120
	v_mul_f32_e32 v135, v135, v135
	v_mul_f32_e32 v133, v133, v133
	v_fmac_f32_e32 v135, v134, v134
	v_fmac_f32_e32 v133, v132, v132
	v_add_f32_e32 v132, v135, v133
	v_add_f32_e32 v131, v132, v131
	v_mov_b32_e32 v132, v131
	v_mov_b32_e32 v212, v131
	s_nop 1
	v_permlane16_swap_b32_e32 v132, v212
	s_waitcnt lgkmcnt(0)
	v_add_f32_e32 v131, v132, v212
	v_mov_b32_e32 v132, v131
	v_mov_b32_e32 v212, v131
	s_nop 1
	v_permlane32_swap_b32_e32 v132, v212
	s_and_saveexec_b64 s[0:1], vcc
	s_cbranch_execz .LBB0_508
	s_lshl_b32 s39, s59, 11
	s_add_i32 s39, s7, s39
	v_mul_f32_e32 v134, 0x3c800000, v129
	v_lshl_add_u32 v129, v175, 5, s39
	s_waitcnt lgkmcnt(0)
	v_add_f32_e32 v135, v132, v212
	ds_write_b64 v129, v[134:135] offset:4608
;     __device__ __forceinline__ bool run(const f32x4 (&v)[2][2][4][2], const Unit& u, int wr, int wc, int fr, int fq, PG8_LAS unsigned char* lds, int wid, int lane) const {
;     ...
;                     for (int n = 0; n < 2; ++n) { const f32x4 x = v[ai][bj][m][n]; s += (x[0] + x[1]) + (x[2] + x[3]); }
;                 s += __shfl_xor(s, 16); s += __shfl_xor(s, 32);
;                 const float mw = s * (1.0f / 64.0f); float q = 0.f;
; #pragma unroll
;                 for (int bj = 0; bj < 2; ++bj)
; #pragma unroll
;                     for (int n = 0; n < 2; ++n) { const f32x4 d = v[ai][bj][m][n] - mw; q += (d[0] * d[0] + d[1] * d[1]) + (d[2] * d[2] + d[3] * d[3]); }
;                 q += __shfl_xor(q, 16); q += __shfl_xor(q, 32);
;                 if (fq == 0) P[(ai * HALF + wr * 64 + m * 16 + fr) * 4 + wc] = (f32x2v){mw, q};
.LBB0_508:
	s_or_b64 exec, exec, s[0:1]
	s_waitcnt lgkmcnt(0)
	v_mov_b32_e32 v132, v45
	v_mov_b32_e32 v133, v46
	v_mov_b32_e32 v134, v44
	v_mov_b32_e32 v135, v47
	v_pk_add_f32 v[132:133], v[132:133], v[134:135]
	v_mov_b32_e32 v134, v25
	v_mov_b32_e32 v135, v26
	v_mov_b32_e32 v136, v24
	v_mov_b32_e32 v137, v27
	v_pk_add_f32 v[134:135], v[134:135], v[136:137]
	v_add_f32_e32 v129, v132, v133
	v_pk_add_f32 v[134:135], v[134:135], v[134:135] op_sel:[0,1] op_sel_hi:[1,0]
	v_add_f32_e32 v132, 0, v129
	v_add_f32_e32 v136, v12, v13
	v_add_f32_e32 v138, v14, v15
	v_mov_b32_e32 v133, v112
	v_mov_b32_e32 v135, v113
	v_mov_b32_e32 v137, v114
	v_mov_b32_e32 v139, v115
	v_pk_add_f32 v[132:133], v[132:133], v[134:135]
	v_pk_add_f32 v[134:135], v[136:137], v[138:139]
	s_nop 0
	v_pk_add_f32 v[132:133], v[132:133], v[134:135]
	s_nop 0
	v_add_f32_e32 v129, v132, v133
	v_mov_b32_e32 v131, v129
	v_mov_b32_e32 v212, v129
	s_nop 1
	v_permlane16_swap_b32_e32 v131, v212
	s_waitcnt lgkmcnt(0)
	v_add_f32_e32 v129, v131, v212
	v_mov_b32_e32 v131, v129
	v_mov_b32_e32 v212, v129
	s_nop 1
	v_permlane32_swap_b32_e32 v131, v212
	s_waitcnt lgkmcnt(0)
	v_add_f32_e32 v129, v131, v212
	v_fmamk_f32 v132, v129, 0xbc800000, v47
	v_fmamk_f32 v134, v129, 0xbc800000, v45
	v_fmamk_f32 v131, v129, 0xbc800000, v46
	v_fmamk_f32 v133, v129, 0xbc800000, v44
	v_mul_f32_e32 v134, v134, v134
	v_mul_f32_e32 v132, v132, v132
	v_fmac_f32_e32 v134, v133, v133
	v_fmac_f32_e32 v132, v131, v131
	v_fmamk_f32 v133, v129, 0xbc800000, v27
	v_fmamk_f32 v135, v129, 0xbc800000, v25
	v_add_f32_e32 v131, v134, v132
	v_fmamk_f32 v132, v129, 0xbc800000, v26
	v_fmamk_f32 v134, v129, 0xbc800000, v24
	v_mul_f32_e32 v135, v135, v135
	v_mul_f32_e32 v133, v133, v133
	v_fmac_f32_e32 v135, v134, v134
	v_fmac_f32_e32 v133, v132, v132
	v_add_f32_e32 v132, v135, v133
	v_fmamk_f32 v133, v129, 0xbc800000, v15
	v_fmamk_f32 v135, v129, 0xbc800000, v13
	v_add_f32_e32 v131, v131, v132
	v_fmamk_f32 v132, v129, 0xbc800000, v14
	v_fmamk_f32 v134, v129, 0xbc800000, v12
	v_mul_f32_e32 v135, v135, v135
	v_mul_f32_e32 v133, v133, v133
	v_fmac_f32_e32 v135, v134, v134
	v_fmac_f32_e32 v133, v132, v132
	v_add_f32_e32 v132, v135, v133
	v_fmamk_f32 v133, v129, 0xbc800000, v115
	v_fmamk_f32 v135, v129, 0xbc800000, v113
	v_add_f32_e32 v131, v132, v131
	v_fmamk_f32 v132, v129, 0xbc800000, v114
	v_fmamk_f32 v134, v129, 0xbc800000, v112
	v_mul_f32_e32 v135, v135, v135
	v_mul_f32_e32 v133, v133, v133
	v_fmac_f32_e32 v135, v134, v134
	v_fmac_f32_e32 v133, v132, v132
	v_add_f32_e32 v132, v135, v133
	v_add_f32_e32 v131, v132, v131
	v_mov_b32_e32 v132, v131
	v_mov_b32_e32 v212, v131
	s_nop 1
	v_permlane16_swap_b32_e32 v132, v212
	s_waitcnt lgkmcnt(0)
	v_add_f32_e32 v131, v132, v212
	v_mov_b32_e32 v132, v131
	v_mov_b32_e32 v212, v131
	s_nop 1
	v_permlane32_swap_b32_e32 v132, v212
	s_and_saveexec_b64 s[0:1], vcc
	s_cbranch_execz .LBB0_510
	s_lshl_b32 s39, s59, 11
	s_add_i32 s39, s7, s39
	v_mul_f32_e32 v134, 0x3c800000, v129
	v_lshl_add_u32 v129, v175, 5, s39
	s_waitcnt lgkmcnt(0)
	v_add_f32_e32 v135, v132, v212
	ds_write_b64 v129, v[134:135] offset:5120
.LBB0_510:
	s_or_b64 exec, exec, s[0:1]
	s_waitcnt lgkmcnt(0)
	v_mov_b32_e32 v132, v29
	v_mov_b32_e32 v133, v30
	v_mov_b32_e32 v134, v28
	v_mov_b32_e32 v135, v31
	v_pk_add_f32 v[132:133], v[132:133], v[134:135]
	v_mov_b32_e32 v134, v9
	v_mov_b32_e32 v135, v10
	v_mov_b32_e32 v136, v8
	v_mov_b32_e32 v137, v11
	v_pk_add_f32 v[134:135], v[134:135], v[136:137]
	v_add_f32_e32 v129, v132, v133
	v_pk_add_f32 v[134:135], v[134:135], v[134:135] op_sel:[0,1] op_sel_hi:[1,0]
	v_add_f32_e32 v132, 0, v129
	v_add_f32_e32 v136, v0, v1
	v_add_f32_e32 v138, v2, v3
	v_mov_b32_e32 v133, v104
	v_mov_b32_e32 v135, v105
	v_mov_b32_e32 v137, v106
	v_mov_b32_e32 v139, v107
	v_pk_add_f32 v[132:133], v[132:133], v[134:135]
	v_pk_add_f32 v[134:135], v[136:137], v[138:139]
	s_nop 0
	v_pk_add_f32 v[132:133], v[132:133], v[134:135]
	s_nop 0
	v_add_f32_e32 v129, v132, v133
	v_mov_b32_e32 v131, v129
	v_mov_b32_e32 v212, v129
	s_nop 1
	v_permlane16_swap_b32_e32 v131, v212
	s_waitcnt lgkmcnt(0)
	v_add_f32_e32 v129, v131, v212
	v_mov_b32_e32 v131, v129
	v_mov_b32_e32 v212, v129
	s_nop 1
	v_permlane32_swap_b32_e32 v131, v212
	s_waitcnt lgkmcnt(0)
	v_add_f32_e32 v129, v131, v212
	v_fmamk_f32 v132, v129, 0xbc800000, v31
	v_fmamk_f32 v134, v129, 0xbc800000, v29
	v_fmamk_f32 v131, v129, 0xbc800000, v30
	v_fmamk_f32 v133, v129, 0xbc800000, v28
	v_mul_f32_e32 v134, v134, v134
	v_mul_f32_e32 v132, v132, v132
	v_fmac_f32_e32 v134, v133, v133
	v_fmac_f32_e32 v132, v131, v131
	v_fmamk_f32 v133, v129, 0xbc800000, v11
	v_fmamk_f32 v135, v129, 0xbc800000, v9
	v_add_f32_e32 v131, v134, v132
	v_fmamk_f32 v132, v129, 0xbc800000, v10
	v_fmamk_f32 v134, v129, 0xbc800000, v8
	v_mul_f32_e32 v135, v135, v135
	v_mul_f32_e32 v133, v133, v133
	v_fmac_f32_e32 v135, v134, v134
	v_fmac_f32_e32 v133, v132, v132
	v_add_f32_e32 v132, v135, v133
	v_fmamk_f32 v133, v129, 0xbc800000, v3
	v_fmamk_f32 v135, v129, 0xbc800000, v1
	v_add_f32_e32 v131, v131, v132
	v_fmamk_f32 v132, v129, 0xbc800000, v2
	v_fmamk_f32 v134, v129, 0xbc800000, v0
	v_mul_f32_e32 v135, v135, v135
	v_mul_f32_e32 v133, v133, v133
	v_fmac_f32_e32 v135, v134, v134
	v_fmac_f32_e32 v133, v132, v132
	v_add_f32_e32 v132, v135, v133
	v_fmamk_f32 v133, v129, 0xbc800000, v107
	v_fmamk_f32 v135, v129, 0xbc800000, v105
	v_add_f32_e32 v131, v132, v131
	v_fmamk_f32 v132, v129, 0xbc800000, v106
	v_fmamk_f32 v134, v129, 0xbc800000, v104
	v_mul_f32_e32 v135, v135, v135
	v_mul_f32_e32 v133, v133, v133
	v_fmac_f32_e32 v135, v134, v134
	v_fmac_f32_e32 v133, v132, v132
	v_add_f32_e32 v132, v135, v133
	v_add_f32_e32 v131, v132, v131
	v_mov_b32_e32 v132, v131
	v_mov_b32_e32 v212, v131
	s_nop 1
	v_permlane16_swap_b32_e32 v132, v212
	s_waitcnt lgkmcnt(0)
	v_add_f32_e32 v131, v132, v212
	v_mov_b32_e32 v128, v131
	v_mov_b32_e32 v212, v131
	s_nop 1
	v_permlane32_swap_b32_e32 v128, v212
	s_and_saveexec_b64 s[0:1], vcc
	s_cbranch_execz .LBB0_512
	s_lshl_b32 s39, s59, 11
	s_add_i32 s7, s7, s39
	v_mul_f32_e32 v132, 0x3c800000, v129
	v_lshl_add_u32 v129, v175, 5, s7
	s_waitcnt lgkmcnt(0)
	v_add_f32_e32 v133, v128, v212
	ds_write_b64 v129, v[132:133] offset:5632
